# slc / win attention steps: wave-uniform need test shortened (v_cndmask + v_cmp_ne ballot replaced by one s_and_b64 with exec), 4 sites, on v25
# baseline (speedup 1.0000x reference)
; #define MFMA32(a, b, c) __builtin_amdgcn_mfma_f32_32x32x16_bf16((a), (b), (c), 0, 0, 0)
; DI void coop_compute(AttnAcc& a, const bf16x8 (&qf)[8], char* stg, const int lo, const int hi, int lane) {
;     ...
;   for (int hf = 0; hf < 2; ++hf) {
;     const char* kr = stg + (32 * hf + u) * KSTR + 16 * h;
;     bf16x8 kf[8];
; #pragma unroll
;     for (int s = 0; s < 8; ++s) kf[s] = *reinterpret_cast<const bf16x8*>(kr + 32 * s);
;     st[hf] = zero16();
; #pragma unroll
;     for (int s = 0; s < 8; ++s) st[hf] = MFMA32(kf[s], qf[s], st[hf]);
;   }
;   constexpr float C2 = SCALE * 1.4426950408889634f;
;   const bool full = (lo <= 0) && (hi >= 63), empty = lo > hi;
;   float mx = a.m;
;   if (__all(full || empty)) {
; DI void slc_block(const Params& p, int it, int tid, int wid, int lane) {
;     ...
;             [&](int j) -> bool { return ((wunion >> j) & 1ull) != 0; },
;             [&](int j, int& lo_, int& hi_) { const bool sel = ((mysel >> j) & 1ull) != 0; const int h0 = t - 64 * j; lo_ = sel ? 0 : 1000; hi_ = sel ? (h0 < 63 ? h0 : 63) : -1000; }, tid, lane);
.LBB0_203:
	s_lshl_b64 s[2:3], 1, s14
	s_and_b64 s[12:13], s[2:3], s[20:21]
	s_cmp_eq_u64 s[12:13], 0
	s_cbranch_scc1 .LBB0_225
	v_add_u32_e32 v0, v217, v218
	ds_read_b128 v[188:191], v0
	ds_read_b128 v[192:195], v0 offset:32
	ds_read_b128 v[196:199], v0 offset:64
	ds_read_b128 v[200:203], v0 offset:96
	ds_read_b128 v[204:207], v0 offset:128
	ds_read_b128 v[208:211], v0 offset:160
	ds_read_b128 v[212:215], v0 offset:192
	ds_read_b128 v[248:251], v0 offset:224
	v_add_u32_e32 v0, v217, v219
	v_and_b32_e32 v14, s2, v184
	s_lshl_b32 s2, s14, 6
	v_and_b32_e32 v15, s3, v165
	s_waitcnt lgkmcnt(7)
	v_mfma_f32_32x32x16_bf16 v[96:111], v[188:191], v[136:139], 0
	ds_read_b128 v[188:191], v0
	v_cmp_eq_u64_e32 vcc, 0, v[14:15]
	s_nop 1
	v_cndmask_b32_e32 v14, 0, v229, vcc
	s_waitcnt lgkmcnt(7)
	v_mfma_f32_32x32x16_bf16 v[96:111], v[192:195], v[112:115], v[96:111]
	ds_read_b128 v[192:195], v0 offset:32
	s_waitcnt lgkmcnt(7)
	v_mfma_f32_32x32x16_bf16 v[96:111], v[196:199], v[116:119], v[96:111]
	ds_read_b128 v[196:199], v0 offset:64
	s_waitcnt lgkmcnt(7)
	v_mfma_f32_32x32x16_bf16 v[96:111], v[200:203], v[120:123], v[96:111]
	ds_read_b128 v[200:203], v0 offset:96
	s_waitcnt lgkmcnt(7)
	v_mfma_f32_32x32x16_bf16 v[96:111], v[204:207], v[124:127], v[96:111]
	ds_read_b128 v[204:207], v0 offset:128
	s_waitcnt lgkmcnt(7)
	v_mfma_f32_32x32x16_bf16 v[96:111], v[208:211], v[128:131], v[96:111]
	ds_read_b128 v[208:211], v0 offset:160
	s_waitcnt lgkmcnt(7)
	v_mfma_f32_32x32x16_bf16 v[96:111], v[212:215], v[132:135], v[96:111]
	ds_read_b128 v[212:215], v0 offset:192
	s_waitcnt lgkmcnt(7)
	v_mfma_f32_32x32x16_bf16 v[96:111], v[248:251], v[140:143], v[96:111]
	ds_read_b128 v[248:251], v0 offset:224
	s_waitcnt lgkmcnt(7)
	v_mfma_f32_32x32x16_bf16 v[80:95], v[188:191], v[136:139], 0
	s_waitcnt lgkmcnt(6)
	v_mfma_f32_32x32x16_bf16 v[80:95], v[192:195], v[112:115], v[80:95]
	s_waitcnt lgkmcnt(5)
	v_mfma_f32_32x32x16_bf16 v[80:95], v[196:199], v[116:119], v[80:95]
	s_waitcnt lgkmcnt(4)
	v_mfma_f32_32x32x16_bf16 v[80:95], v[200:203], v[120:123], v[80:95]
	s_waitcnt lgkmcnt(3)
	v_mfma_f32_32x32x16_bf16 v[80:95], v[204:207], v[124:127], v[80:95]
	v_subrev_u32_e32 v186, s2, v182
	v_min_i32_e32 v186, 63, v186
	v_cndmask_b32_e32 v15, v186, v230, vcc
	v_cmp_lt_i32_e64 s[12:13], 62, v15
	v_cmp_gt_i32_e64 s[14:15], v14, v15
	s_or_b64 s[2:3], s[14:15], s[12:13]
	s_waitcnt lgkmcnt(2)
	v_mfma_f32_32x32x16_bf16 v[80:95], v[208:211], v[128:131], v[80:95]
	s_and_b64 s[16:17], s[2:3], exec
	s_mov_b64 s[2:3], -1
	s_cmp_lg_u64 s[16:17], exec
	s_waitcnt lgkmcnt(1)
	v_mfma_f32_32x32x16_bf16 v[80:95], v[212:215], v[132:135], v[80:95]
	s_waitcnt lgkmcnt(0)
	v_mfma_f32_32x32x16_bf16 v[80:95], v[248:251], v[140:143], v[80:95]
	s_cbranch_scc0 .LBB0_206
; DI void coop_compute(AttnAcc& a, const bf16x8 (&qf)[8], char* stg, const int lo, const int hi, int lane) {
;     ...
;     const unsigned span = empty ? 0u : (unsigned)(hi - lo);
;     const int lo3 = empty ? (1 << 20) : lo - 4 * h;
; #pragma unroll
;     for (int hf = 0; hf < 2; ++hf)
; #pragma unroll
;       for (int i = 0; i < 16; ++i) {
;         const int vc = 32 * hf + (i & 3) + 8 * (i >> 2);
;         const bool ok = (unsigned)(vc - lo3) <= span;
;         const float sv = ok ? st[hf][i] * C2 : NEG;
;         st[hf][i] = sv; mx = fmaxf(mx, sv);
;       }
;   }
	v_mov_b32_e32 v0, 0xfffff830
	v_cndmask_b32_e32 v0, v186, v0, vcc
	v_sub_u32_e32 v14, v220, v14
	v_cndmask_b32_e64 v0, v0, 0, s[14:15]
	v_cndmask_b32_e64 v222, v14, v232, s[14:15]
	v_mul_f32_e32 v14, 0x3e0293ee, v96
	v_cmp_le_u32_e32 vcc, v222, v0
	v_mul_f32_e32 v15, 0x3e0293ee, v97
	v_or_b32_e32 v189, 3, v222
	v_cndmask_b32_e32 v14, v233, v14, vcc
	v_cmp_lt_u32_e32 vcc, v222, v0
	v_pk_mul_f32 v[186:187], v[98:99], s[44:45] op_sel_hi:[1,0]
	v_or_b32_e32 v190, 2, v222
	v_cndmask_b32_e32 v15, v233, v15, vcc
	v_cmp_le_u32_e32 vcc, v189, v0
	v_max3_f32 v188, v183, v14, v15
	v_add_u32_e32 v192, 9, v222
	v_cndmask_b32_e32 v187, v233, v187, vcc
	v_cmp_le_u32_e32 vcc, v190, v0
	v_add_u32_e32 v191, 8, v222
	v_add_u32_e32 v194, 11, v222
	v_cndmask_b32_e32 v186, v233, v186, vcc
	v_max3_f32 v190, v188, v186, v187
	v_pk_mul_f32 v[188:189], v[100:101], s[44:45] op_sel_hi:[1,0]
	v_cmp_le_u32_e32 vcc, v192, v0
	v_add_u32_e32 v193, 10, v222
	v_add_u32_e32 v196, 17, v222
	v_cndmask_b32_e32 v189, v233, v189, vcc
	v_cmp_le_u32_e32 vcc, v191, v0
	v_add_u32_e32 v195, 16, v222
	v_add_u32_e32 v198, 19, v222
	v_cndmask_b32_e32 v188, v233, v188, vcc
	v_max3_f32 v192, v190, v188, v189
	v_pk_mul_f32 v[190:191], v[102:103], s[44:45] op_sel_hi:[1,0]
	v_cmp_le_u32_e32 vcc, v194, v0
	v_add_u32_e32 v197, 18, v222
	v_add_u32_e32 v200, 25, v222
	v_cndmask_b32_e32 v191, v233, v191, vcc
	v_cmp_le_u32_e32 vcc, v193, v0
	v_add_u32_e32 v199, 24, v222
	v_add_u32_e32 v202, 27, v222
	v_cndmask_b32_e32 v190, v233, v190, vcc
	v_max3_f32 v194, v192, v190, v191
	v_pk_mul_f32 v[192:193], v[104:105], s[44:45] op_sel_hi:[1,0]
	v_cmp_le_u32_e32 vcc, v196, v0
	v_add_u32_e32 v201, 26, v222
	v_add_u32_e32 v204, 33, v222
	v_cndmask_b32_e32 v193, v233, v193, vcc
	v_cmp_le_u32_e32 vcc, v195, v0
	v_add_u32_e32 v203, 32, v222
	v_add_u32_e32 v206, 35, v222
	v_cndmask_b32_e32 v192, v233, v192, vcc
	v_max3_f32 v196, v194, v192, v193
	v_pk_mul_f32 v[194:195], v[106:107], s[44:45] op_sel_hi:[1,0]
	v_cmp_le_u32_e32 vcc, v198, v0
	v_add_u32_e32 v205, 34, v222
	v_add_u32_e32 v208, 41, v222
	v_cndmask_b32_e32 v195, v233, v195, vcc
	v_cmp_le_u32_e32 vcc, v197, v0
	v_add_u32_e32 v207, 40, v222
	v_add_u32_e32 v210, 43, v222
	v_cndmask_b32_e32 v194, v233, v194, vcc
	v_max3_f32 v198, v196, v194, v195
	v_pk_mul_f32 v[196:197], v[108:109], s[44:45] op_sel_hi:[1,0]
	v_cmp_le_u32_e32 vcc, v200, v0
	v_add_u32_e32 v209, 42, v222
	v_add_u32_e32 v212, 49, v222
	v_cndmask_b32_e32 v197, v233, v197, vcc
	v_cmp_le_u32_e32 vcc, v199, v0
	v_add_u32_e32 v211, 48, v222
	v_add_u32_e32 v214, 51, v222
	v_cndmask_b32_e32 v196, v233, v196, vcc
	v_max3_f32 v200, v198, v196, v197
	v_pk_mul_f32 v[198:199], v[110:111], s[44:45] op_sel_hi:[1,0]
	v_cmp_le_u32_e32 vcc, v202, v0
	v_add_u32_e32 v213, 50, v222
	v_add_u32_e32 v223, 57, v222
	v_cndmask_b32_e32 v199, v233, v199, vcc
	v_cmp_le_u32_e32 vcc, v201, v0
	v_add_u32_e32 v215, 56, v222
	v_add_u32_e32 v224, 58, v222
	v_cndmask_b32_e32 v198, v233, v198, vcc
	v_max3_f32 v202, v200, v198, v199
	v_pk_mul_f32 v[200:201], v[80:81], s[44:45] op_sel_hi:[1,0]
	v_cmp_le_u32_e32 vcc, v204, v0
	v_add_u32_e32 v222, 59, v222
	s_mov_b64 s[2:3], 0
	v_cndmask_b32_e32 v201, v233, v201, vcc
	v_cmp_le_u32_e32 vcc, v203, v0
	s_nop 1
	v_cndmask_b32_e32 v200, v233, v200, vcc
	v_max3_f32 v204, v202, v200, v201
	v_pk_mul_f32 v[202:203], v[82:83], s[44:45] op_sel_hi:[1,0]
	v_cmp_le_u32_e32 vcc, v206, v0
	s_nop 1
	v_cndmask_b32_e32 v203, v233, v203, vcc
	v_cmp_le_u32_e32 vcc, v205, v0
	s_nop 1
	v_cndmask_b32_e32 v202, v233, v202, vcc
	v_max3_f32 v206, v204, v202, v203
	v_pk_mul_f32 v[204:205], v[84:85], s[44:45] op_sel_hi:[1,0]
	v_cmp_le_u32_e32 vcc, v208, v0
	s_nop 1
	v_cndmask_b32_e32 v205, v233, v205, vcc
	v_cmp_le_u32_e32 vcc, v207, v0
	s_nop 1
	v_cndmask_b32_e32 v204, v233, v204, vcc
	v_max3_f32 v208, v206, v204, v205
	v_pk_mul_f32 v[206:207], v[86:87], s[44:45] op_sel_hi:[1,0]
	v_cmp_le_u32_e32 vcc, v210, v0
	s_nop 1
	v_cndmask_b32_e32 v207, v233, v207, vcc
	v_cmp_le_u32_e32 vcc, v209, v0
	s_nop 1
	v_cndmask_b32_e32 v206, v233, v206, vcc
	v_max3_f32 v210, v208, v206, v207
	v_pk_mul_f32 v[208:209], v[88:89], s[44:45] op_sel_hi:[1,0]
	v_cmp_le_u32_e32 vcc, v212, v0
	s_nop 1
	v_cndmask_b32_e32 v209, v233, v209, vcc
	v_cmp_le_u32_e32 vcc, v211, v0
	s_nop 1
	v_cndmask_b32_e32 v208, v233, v208, vcc
	v_max3_f32 v212, v210, v208, v209
	v_pk_mul_f32 v[210:211], v[90:91], s[44:45] op_sel_hi:[1,0]
	v_cmp_le_u32_e32 vcc, v214, v0
	s_nop 1
	v_cndmask_b32_e32 v211, v233, v211, vcc
	v_cmp_le_u32_e32 vcc, v213, v0
	s_nop 1
	v_cndmask_b32_e32 v210, v233, v210, vcc
	v_max3_f32 v214, v212, v210, v211
	v_pk_mul_f32 v[212:213], v[92:93], s[44:45] op_sel_hi:[1,0]
	v_cmp_le_u32_e32 vcc, v223, v0
	s_nop 1
	v_cndmask_b32_e32 v213, v233, v213, vcc
	v_cmp_le_u32_e32 vcc, v215, v0
	s_nop 1
	v_cndmask_b32_e32 v212, v233, v212, vcc
	v_max3_f32 v223, v214, v212, v213
	v_pk_mul_f32 v[214:215], v[94:95], s[44:45] op_sel_hi:[1,0]
	v_cmp_le_u32_e32 vcc, v222, v0
	s_nop 1
	v_cndmask_b32_e32 v215, v233, v215, vcc
	v_cmp_le_u32_e32 vcc, v224, v0
	s_nop 1
	v_cndmask_b32_e32 v214, v233, v214, vcc
	v_max3_f32 v0, v223, v214, v215

; #define MFMA32(a, b, c) __builtin_amdgcn_mfma_f32_32x32x16_bf16((a), (b), (c), 0, 0, 0)
; DI void coop_compute(AttnAcc& a, const bf16x8 (&qf)[8], char* stg, const int lo, const int hi, int lane) {
;     ...
;   for (int hf = 0; hf < 2; ++hf) {
;     const char* kr = stg + (32 * hf + u) * KSTR + 16 * h;
;     bf16x8 kf[8];
; #pragma unroll
;     for (int s = 0; s < 8; ++s) kf[s] = *reinterpret_cast<const bf16x8*>(kr + 32 * s);
;     st[hf] = zero16();
; #pragma unroll
;     for (int s = 0; s < 8; ++s) st[hf] = MFMA32(kf[s], qf[s], st[hf]);
;   }
;   constexpr float C2 = SCALE * 1.4426950408889634f;
;   const bool full = (lo <= 0) && (hi >= 63), empty = lo > hi;
;   float mx = a.m;
;   if (__all(full || empty)) {
; DI void slc_block(const Params& p, int it, int tid, int wid, int lane) {
;     ...
;             [&](int j) -> bool { return ((wunion >> j) & 1ull) != 0; },
;             [&](int j, int& lo_, int& hi_) { const bool sel = ((mysel >> j) & 1ull) != 0; const int h0 = t - 64 * j; lo_ = sel ? 0 : 1000; hi_ = sel ? (h0 < 63 ? h0 : 63) : -1000; }, tid, lane);
.LBB0_215:
	s_lshl_b64 s[2:3], 1, s11
	s_and_b64 s[12:13], s[2:3], s[20:21]
	s_cmp_eq_u64 s[12:13], 0
	s_cbranch_scc1 .LBB0_226
	v_add_u32_e32 v0, v217, v218
	ds_read_b128 v[188:191], v0 offset:35840
	ds_read_b128 v[192:195], v0 offset:35872
	ds_read_b128 v[196:199], v0 offset:35904
	ds_read_b128 v[200:203], v0 offset:35936
	ds_read_b128 v[204:207], v0 offset:35968
	ds_read_b128 v[208:211], v0 offset:36000
	ds_read_b128 v[212:215], v0 offset:36032
	ds_read_b128 v[248:251], v0 offset:36064
	v_add_u32_e32 v0, v217, v219
	v_and_b32_e32 v14, s2, v184
	s_lshl_b32 s2, s11, 6
	v_and_b32_e32 v15, s3, v165
	s_waitcnt lgkmcnt(7)
	v_mfma_f32_32x32x16_bf16 v[96:111], v[188:191], v[136:139], 0
	ds_read_b128 v[188:191], v0 offset:35840
	v_subrev_u32_e32 v183, s2, v182
	v_cmp_eq_u64_e32 vcc, 0, v[14:15]
	v_min_i32_e32 v183, 63, v183
	s_nop 0
	v_cndmask_b32_e32 v14, 0, v229, vcc
	v_cndmask_b32_e32 v15, v183, v230, vcc
	s_waitcnt lgkmcnt(7)
	v_mfma_f32_32x32x16_bf16 v[96:111], v[192:195], v[112:115], v[96:111]
	ds_read_b128 v[192:195], v0 offset:35872
	v_cmp_lt_i32_e64 s[12:13], 62, v15
	v_cmp_gt_i32_e64 s[14:15], v14, v15
	s_or_b64 s[2:3], s[14:15], s[12:13]
	s_waitcnt lgkmcnt(7)
	v_mfma_f32_32x32x16_bf16 v[96:111], v[196:199], v[116:119], v[96:111]
	ds_read_b128 v[196:199], v0 offset:35904
	s_waitcnt lgkmcnt(7)
	v_mfma_f32_32x32x16_bf16 v[96:111], v[200:203], v[120:123], v[96:111]
	ds_read_b128 v[200:203], v0 offset:35936
	s_waitcnt lgkmcnt(7)
	v_mfma_f32_32x32x16_bf16 v[96:111], v[204:207], v[124:127], v[96:111]
	ds_read_b128 v[204:207], v0 offset:35968
	s_waitcnt lgkmcnt(7)
	v_mfma_f32_32x32x16_bf16 v[96:111], v[208:211], v[128:131], v[96:111]
	ds_read_b128 v[208:211], v0 offset:36000
	s_waitcnt lgkmcnt(7)
	v_mfma_f32_32x32x16_bf16 v[96:111], v[212:215], v[132:135], v[96:111]
	ds_read_b128 v[212:215], v0 offset:36032
	s_waitcnt lgkmcnt(7)
	v_mfma_f32_32x32x16_bf16 v[96:111], v[248:251], v[140:143], v[96:111]
	ds_read_b128 v[248:251], v0 offset:36064
	s_waitcnt lgkmcnt(7)
	v_mfma_f32_32x32x16_bf16 v[80:95], v[188:191], v[136:139], 0
	s_waitcnt lgkmcnt(6)
	v_mfma_f32_32x32x16_bf16 v[80:95], v[192:195], v[112:115], v[80:95]
	s_waitcnt lgkmcnt(5)
	v_mfma_f32_32x32x16_bf16 v[80:95], v[196:199], v[116:119], v[80:95]
	s_waitcnt lgkmcnt(4)
	v_mfma_f32_32x32x16_bf16 v[80:95], v[200:203], v[120:123], v[80:95]
	s_waitcnt lgkmcnt(3)
	v_mfma_f32_32x32x16_bf16 v[80:95], v[204:207], v[124:127], v[80:95]
	s_waitcnt lgkmcnt(2)
	v_mfma_f32_32x32x16_bf16 v[80:95], v[208:211], v[128:131], v[80:95]
	s_and_b64 s[16:17], s[2:3], exec
	s_mov_b64 s[2:3], -1
	s_cmp_lg_u64 s[16:17], exec
	s_waitcnt lgkmcnt(1)
	v_mfma_f32_32x32x16_bf16 v[80:95], v[212:215], v[132:135], v[80:95]
	s_waitcnt lgkmcnt(0)
	v_mfma_f32_32x32x16_bf16 v[80:95], v[248:251], v[140:143], v[80:95]
	s_cbranch_scc0 .LBB0_218
; DI void coop_compute(AttnAcc& a, const bf16x8 (&qf)[8], char* stg, const int lo, const int hi, int lane) {
;     ...
;     const unsigned span = empty ? 0u : (unsigned)(hi - lo);
;     const int lo3 = empty ? (1 << 20) : lo - 4 * h;
; #pragma unroll
;     for (int hf = 0; hf < 2; ++hf)
; #pragma unroll
;       for (int i = 0; i < 16; ++i) {
;         const int vc = 32 * hf + (i & 3) + 8 * (i >> 2);
;         const bool ok = (unsigned)(vc - lo3) <= span;
;         const float sv = ok ? st[hf][i] * C2 : NEG;
;         st[hf][i] = sv; mx = fmaxf(mx, sv);
;       }
;   }
	v_mov_b32_e32 v0, 0xfffff830
	v_cndmask_b32_e32 v0, v183, v0, vcc
	v_sub_u32_e32 v14, v220, v14
	v_cndmask_b32_e64 v0, v0, 0, s[14:15]
	v_cndmask_b32_e64 v183, v14, v232, s[14:15]
	v_mul_f32_e32 v14, 0x3e0293ee, v96
	v_cmp_le_u32_e32 vcc, v183, v0
	v_mul_f32_e32 v15, 0x3e0293ee, v97
	v_or_b32_e32 v189, 3, v183
	v_cndmask_b32_e32 v14, v233, v14, vcc
	v_cmp_lt_u32_e32 vcc, v183, v0
	v_pk_mul_f32 v[186:187], v[98:99], s[44:45] op_sel_hi:[1,0]
	v_or_b32_e32 v190, 2, v183
	v_cndmask_b32_e32 v15, v233, v15, vcc
	v_cmp_le_u32_e32 vcc, v189, v0
	v_max3_f32 v188, v223, v14, v15
	v_add_u32_e32 v192, 9, v183
	v_cndmask_b32_e32 v187, v233, v187, vcc
	v_cmp_le_u32_e32 vcc, v190, v0
	v_add_u32_e32 v191, 8, v183
	v_add_u32_e32 v194, 11, v183
	v_cndmask_b32_e32 v186, v233, v186, vcc
	v_max3_f32 v190, v188, v186, v187
	v_pk_mul_f32 v[188:189], v[100:101], s[44:45] op_sel_hi:[1,0]
	v_cmp_le_u32_e32 vcc, v192, v0
	v_add_u32_e32 v193, 10, v183
	v_add_u32_e32 v196, 17, v183
	v_cndmask_b32_e32 v189, v233, v189, vcc
	v_cmp_le_u32_e32 vcc, v191, v0
	v_add_u32_e32 v195, 16, v183
	v_add_u32_e32 v198, 19, v183
	v_cndmask_b32_e32 v188, v233, v188, vcc
	v_max3_f32 v192, v190, v188, v189
	v_pk_mul_f32 v[190:191], v[102:103], s[44:45] op_sel_hi:[1,0]
	v_cmp_le_u32_e32 vcc, v194, v0
	v_add_u32_e32 v197, 18, v183
	v_add_u32_e32 v200, 25, v183
	v_cndmask_b32_e32 v191, v233, v191, vcc
	v_cmp_le_u32_e32 vcc, v193, v0
	v_add_u32_e32 v199, 24, v183
	v_add_u32_e32 v202, 27, v183
	v_cndmask_b32_e32 v190, v233, v190, vcc
	v_max3_f32 v194, v192, v190, v191
	v_pk_mul_f32 v[192:193], v[104:105], s[44:45] op_sel_hi:[1,0]
	v_cmp_le_u32_e32 vcc, v196, v0
	v_add_u32_e32 v201, 26, v183
	v_add_u32_e32 v204, 33, v183
	v_cndmask_b32_e32 v193, v233, v193, vcc
	v_cmp_le_u32_e32 vcc, v195, v0
	v_add_u32_e32 v203, 32, v183
	v_add_u32_e32 v206, 35, v183
	v_cndmask_b32_e32 v192, v233, v192, vcc
	v_max3_f32 v196, v194, v192, v193
	v_pk_mul_f32 v[194:195], v[106:107], s[44:45] op_sel_hi:[1,0]
	v_cmp_le_u32_e32 vcc, v198, v0
	v_add_u32_e32 v205, 34, v183
	v_add_u32_e32 v208, 41, v183
	v_cndmask_b32_e32 v195, v233, v195, vcc
	v_cmp_le_u32_e32 vcc, v197, v0
	v_add_u32_e32 v207, 40, v183
	v_add_u32_e32 v210, 43, v183
	v_cndmask_b32_e32 v194, v233, v194, vcc
	v_max3_f32 v198, v196, v194, v195
	v_pk_mul_f32 v[196:197], v[108:109], s[44:45] op_sel_hi:[1,0]
	v_cmp_le_u32_e32 vcc, v200, v0
	v_add_u32_e32 v209, 42, v183
	v_add_u32_e32 v212, 49, v183
	v_cndmask_b32_e32 v197, v233, v197, vcc
	v_cmp_le_u32_e32 vcc, v199, v0
	v_add_u32_e32 v211, 48, v183
	v_add_u32_e32 v214, 51, v183
	v_cndmask_b32_e32 v196, v233, v196, vcc
	v_max3_f32 v200, v198, v196, v197
	v_pk_mul_f32 v[198:199], v[110:111], s[44:45] op_sel_hi:[1,0]
	v_cmp_le_u32_e32 vcc, v202, v0
	v_add_u32_e32 v213, 50, v183
	v_add_u32_e32 v222, 57, v183
	v_cndmask_b32_e32 v199, v233, v199, vcc
	v_cmp_le_u32_e32 vcc, v201, v0
	v_add_u32_e32 v215, 56, v183
	v_add_u32_e32 v224, 58, v183
	v_cndmask_b32_e32 v198, v233, v198, vcc
	v_max3_f32 v202, v200, v198, v199
	v_pk_mul_f32 v[200:201], v[80:81], s[44:45] op_sel_hi:[1,0]
	v_cmp_le_u32_e32 vcc, v204, v0
	v_add_u32_e32 v183, 59, v183
	s_mov_b64 s[2:3], 0
	v_cndmask_b32_e32 v201, v233, v201, vcc
	v_cmp_le_u32_e32 vcc, v203, v0
	s_nop 1
	v_cndmask_b32_e32 v200, v233, v200, vcc
	v_max3_f32 v204, v202, v200, v201
	v_pk_mul_f32 v[202:203], v[82:83], s[44:45] op_sel_hi:[1,0]
	v_cmp_le_u32_e32 vcc, v206, v0
	s_nop 1
	v_cndmask_b32_e32 v203, v233, v203, vcc
	v_cmp_le_u32_e32 vcc, v205, v0
	s_nop 1
	v_cndmask_b32_e32 v202, v233, v202, vcc
	v_max3_f32 v206, v204, v202, v203
	v_pk_mul_f32 v[204:205], v[84:85], s[44:45] op_sel_hi:[1,0]
	v_cmp_le_u32_e32 vcc, v208, v0
	s_nop 1
	v_cndmask_b32_e32 v205, v233, v205, vcc
	v_cmp_le_u32_e32 vcc, v207, v0
	s_nop 1
	v_cndmask_b32_e32 v204, v233, v204, vcc
	v_max3_f32 v208, v206, v204, v205
	v_pk_mul_f32 v[206:207], v[86:87], s[44:45] op_sel_hi:[1,0]
	v_cmp_le_u32_e32 vcc, v210, v0
	s_nop 1
	v_cndmask_b32_e32 v207, v233, v207, vcc
	v_cmp_le_u32_e32 vcc, v209, v0
	s_nop 1
	v_cndmask_b32_e32 v206, v233, v206, vcc
	v_max3_f32 v210, v208, v206, v207
	v_pk_mul_f32 v[208:209], v[88:89], s[44:45] op_sel_hi:[1,0]
	v_cmp_le_u32_e32 vcc, v212, v0
	s_nop 1
	v_cndmask_b32_e32 v209, v233, v209, vcc
	v_cmp_le_u32_e32 vcc, v211, v0
	s_nop 1
	v_cndmask_b32_e32 v208, v233, v208, vcc
	v_max3_f32 v212, v210, v208, v209
	v_pk_mul_f32 v[210:211], v[90:91], s[44:45] op_sel_hi:[1,0]
	v_cmp_le_u32_e32 vcc, v214, v0
	s_nop 1
	v_cndmask_b32_e32 v211, v233, v211, vcc
	v_cmp_le_u32_e32 vcc, v213, v0
	s_nop 1
	v_cndmask_b32_e32 v210, v233, v210, vcc
	v_max3_f32 v214, v212, v210, v211
	v_pk_mul_f32 v[212:213], v[92:93], s[44:45] op_sel_hi:[1,0]
	v_cmp_le_u32_e32 vcc, v222, v0
	s_nop 1
	v_cndmask_b32_e32 v213, v233, v213, vcc
	v_cmp_le_u32_e32 vcc, v215, v0
	s_nop 1
	v_cndmask_b32_e32 v212, v233, v212, vcc
	v_max3_f32 v222, v214, v212, v213
	v_pk_mul_f32 v[214:215], v[94:95], s[44:45] op_sel_hi:[1,0]
	v_cmp_le_u32_e32 vcc, v183, v0
	s_nop 1
	v_cndmask_b32_e32 v215, v233, v215, vcc
	v_cmp_le_u32_e32 vcc, v224, v0
	s_nop 1
	v_cndmask_b32_e32 v214, v233, v214, vcc
	v_max3_f32 v0, v222, v214, v215

; #define MFMA32(a, b, c) __builtin_amdgcn_mfma_f32_32x32x16_bf16((a), (b), (c), 0, 0, 0)
; DI void coop_compute(AttnAcc& a, const bf16x8 (&qf)[8], char* stg, const int lo, const int hi, int lane) {
;     ...
;   for (int hf = 0; hf < 2; ++hf) {
;     const char* kr = stg + (32 * hf + u) * KSTR + 16 * h;
;     bf16x8 kf[8];
; #pragma unroll
;     for (int s = 0; s < 8; ++s) kf[s] = *reinterpret_cast<const bf16x8*>(kr + 32 * s);
;     st[hf] = zero16();
; #pragma unroll
;     for (int s = 0; s < 8; ++s) st[hf] = MFMA32(kf[s], qf[s], st[hf]);
;   }
;   constexpr float C2 = SCALE * 1.4426950408889634f;
;   const bool full = (lo <= 0) && (hi >= 63), empty = lo > hi;
;   float mx = a.m;
;   if (__all(full || empty)) {
; DI void win_block(const Params& p, int it, int tid, int wid, int lane) {
;     ...
;             [&](int j, int& lo_, int& hi_) { const int l0 = t - 511 - 64 * j, h0 = t - 64 * j; lo_ = l0 > 0 ? l0 : 0; hi_ = h0 < 63 ? h0 : 63; }, tid, lane);
.LBB0_246:
	ds_read_b128 v[66:69], v228
	ds_read_b128 v[70:73], v228 offset:32
	s_lshl_b32 s0, s2, 6
	v_subrev_u32_e32 v175, s0, v188
	v_add_u32_e32 v183, 0xfffffe01, v175
	s_waitcnt lgkmcnt(1)
	v_mfma_f32_32x32x16_bf16 v[82:97], v[66:69], v[122:125], 0
	v_max_i32_e32 v183, 0, v183
	v_min_i32_e32 v185, 63, v175
	v_subrev_u32_e32 v175, 63, v175
	v_cmp_gt_u32_e64 s[0:1], s50, v175
	v_cmp_lt_i32_e32 vcc, v185, v183
	s_or_b64 s[2:3], s[0:1], vcc
	s_waitcnt lgkmcnt(0)
	v_mfma_f32_32x32x16_bf16 v[82:97], v[70:73], v[98:101], v[82:97]
	ds_read_b128 v[66:69], v228 offset:64
	ds_read_b128 v[70:73], v228 offset:96
	s_and_b64 s[4:5], s[2:3], exec
	s_mov_b64 s[2:3], -1
	s_cmp_lg_u64 s[4:5], exec
	s_waitcnt lgkmcnt(1)
	v_mfma_f32_32x32x16_bf16 v[82:97], v[66:69], v[102:105], v[82:97]
	s_waitcnt lgkmcnt(0)
	v_mfma_f32_32x32x16_bf16 v[82:97], v[70:73], v[106:109], v[82:97]
	ds_read_b128 v[66:69], v228 offset:128
	ds_read_b128 v[70:73], v228 offset:160
	s_waitcnt lgkmcnt(1)
	v_mfma_f32_32x32x16_bf16 v[82:97], v[66:69], v[110:113], v[82:97]
	s_waitcnt lgkmcnt(0)
	v_mfma_f32_32x32x16_bf16 v[82:97], v[70:73], v[114:117], v[82:97]
	ds_read_b128 v[66:69], v228 offset:192
	ds_read_b128 v[70:73], v228 offset:224
	s_waitcnt lgkmcnt(1)
	v_mfma_f32_32x32x16_bf16 v[82:97], v[66:69], v[118:121], v[82:97]
	ds_read_b128 v[66:69], v223
	ds_read_b128 v[190:193], v223 offset:32
	s_waitcnt lgkmcnt(2)
	v_mfma_f32_32x32x16_bf16 v[82:97], v[70:73], v[126:129], v[82:97]
	s_waitcnt lgkmcnt(1)
	v_mfma_f32_32x32x16_bf16 v[66:81], v[66:69], v[122:125], 0
	s_waitcnt lgkmcnt(0)
	v_mfma_f32_32x32x16_bf16 v[66:81], v[190:193], v[98:101], v[66:81]
	ds_read_b128 v[190:193], v223 offset:64
	ds_read_b128 v[194:197], v223 offset:96
	s_waitcnt lgkmcnt(1)
	v_mfma_f32_32x32x16_bf16 v[66:81], v[190:193], v[102:105], v[66:81]
	s_waitcnt lgkmcnt(0)
	v_mfma_f32_32x32x16_bf16 v[66:81], v[194:197], v[106:109], v[66:81]
	ds_read_b128 v[190:193], v223 offset:128
	ds_read_b128 v[194:197], v223 offset:160
	ds_read_b128 v[250:253], v223 offset:224
	s_waitcnt lgkmcnt(2)
	v_mfma_f32_32x32x16_bf16 v[66:81], v[190:193], v[110:113], v[66:81]
	ds_read_b128 v[190:193], v223 offset:192
	s_waitcnt lgkmcnt(2)
	v_mfma_f32_32x32x16_bf16 v[66:81], v[194:197], v[114:117], v[66:81]
	s_waitcnt lgkmcnt(0)
	v_mfma_f32_32x32x16_bf16 v[66:81], v[190:193], v[118:121], v[66:81]
	v_mfma_f32_32x32x16_bf16 v[66:81], v[250:253], v[126:129], v[66:81]
	s_cbranch_scc0 .LBB0_248
; DI void coop_compute(AttnAcc& a, const bf16x8 (&qf)[8], char* stg, const int lo, const int hi, int lane) {
;     ...
;     const unsigned span = empty ? 0u : (unsigned)(hi - lo);
;     const int lo3 = empty ? (1 << 20) : lo - 4 * h;
; #pragma unroll
;     for (int hf = 0; hf < 2; ++hf)
; #pragma unroll
;       for (int i = 0; i < 16; ++i) {
;         const int vc = 32 * hf + (i & 3) + 8 * (i >> 2);
;         const bool ok = (unsigned)(vc - lo3) <= span;
;         const float sv = ok ? st[hf][i] * C2 : NEG;
;         st[hf][i] = sv; mx = fmaxf(mx, sv);
;       }
;   }
	v_sub_u32_e32 v175, v185, v183
	v_sub_u32_e32 v183, v243, v183
	v_cndmask_b32_e64 v175, v175, 0, vcc
	v_cndmask_b32_e32 v183, v183, v232, vcc
	v_pk_mul_f32 v[190:191], v[82:83], s[44:45] op_sel_hi:[1,0]
	v_add_u32_e32 v185, 1, v183
	v_cmp_le_u32_e32 vcc, v183, v175
	v_add_u32_e32 v194, 3, v183
	v_pk_mul_f32 v[192:193], v[84:85], s[44:45] op_sel_hi:[1,0]
	v_cndmask_b32_e32 v190, v233, v190, vcc
	v_cmp_le_u32_e32 vcc, v185, v175
	v_add_u32_e32 v189, 2, v183
	v_add_u32_e32 v196, 9, v183
	v_cndmask_b32_e32 v191, v233, v191, vcc
	v_cmp_le_u32_e32 vcc, v194, v175
	v_pk_mul_f32 v[194:195], v[86:87], s[44:45] op_sel_hi:[1,0]
	v_add_u32_e32 v198, 11, v183
	v_cndmask_b32_e32 v193, v233, v193, vcc
	v_cmp_le_u32_e32 vcc, v189, v175
	v_add_u32_e32 v189, 8, v183
	v_add_u32_e32 v200, 17, v183
	v_cndmask_b32_e32 v192, v233, v192, vcc
	v_cmp_le_u32_e32 vcc, v196, v175
	v_pk_mul_f32 v[196:197], v[88:89], s[44:45] op_sel_hi:[1,0]
	v_add_u32_e32 v202, 19, v183
	v_cndmask_b32_e32 v195, v233, v195, vcc
	v_cmp_le_u32_e32 vcc, v189, v175
	v_add_u32_e32 v189, 10, v183
	v_add_u32_e32 v204, 25, v183
	v_cndmask_b32_e32 v194, v233, v194, vcc
	v_cmp_le_u32_e32 vcc, v198, v175
	v_pk_mul_f32 v[198:199], v[90:91], s[44:45] op_sel_hi:[1,0]
	v_add_u32_e32 v206, 27, v183
	v_cndmask_b32_e32 v197, v233, v197, vcc
	v_cmp_le_u32_e32 vcc, v189, v175
	v_add_u32_e32 v189, 16, v183
	v_add_u32_e32 v208, 33, v183
	v_cndmask_b32_e32 v196, v233, v196, vcc
	v_cmp_le_u32_e32 vcc, v200, v175
	v_pk_mul_f32 v[200:201], v[92:93], s[44:45] op_sel_hi:[1,0]
	v_add_u32_e32 v210, 35, v183
	v_cndmask_b32_e32 v199, v233, v199, vcc
	v_cmp_le_u32_e32 vcc, v189, v175
	v_add_u32_e32 v189, 18, v183
	v_max3_f32 v185, v177, v190, v191
	v_cndmask_b32_e32 v198, v233, v198, vcc
	v_cmp_le_u32_e32 vcc, v202, v175
	v_pk_mul_f32 v[202:203], v[94:95], s[44:45] op_sel_hi:[1,0]
	v_max3_f32 v185, v185, v192, v193
	v_cndmask_b32_e32 v201, v233, v201, vcc
	v_cmp_le_u32_e32 vcc, v189, v175
	v_add_u32_e32 v189, 24, v183
	v_add_u32_e32 v212, 41, v183
	v_cndmask_b32_e32 v200, v233, v200, vcc
	v_cmp_le_u32_e32 vcc, v204, v175
	v_pk_mul_f32 v[204:205], v[96:97], s[44:45] op_sel_hi:[1,0]
	v_max3_f32 v185, v185, v194, v195
	v_cndmask_b32_e32 v203, v233, v203, vcc
	v_cmp_le_u32_e32 vcc, v189, v175
	v_add_u32_e32 v189, 26, v183
	v_max3_f32 v185, v185, v196, v197
	v_cndmask_b32_e32 v202, v233, v202, vcc
	v_cmp_le_u32_e32 vcc, v206, v175
	v_pk_mul_f32 v[206:207], v[66:67], s[44:45] op_sel_hi:[1,0]
	v_add_u32_e32 v214, 43, v183
	v_cndmask_b32_e32 v205, v233, v205, vcc
	v_cmp_le_u32_e32 vcc, v189, v175
	v_add_u32_e32 v189, 32, v183
	v_max3_f32 v185, v185, v198, v199
	v_cndmask_b32_e32 v204, v233, v204, vcc
	v_cmp_le_u32_e32 vcc, v208, v175
	v_pk_mul_f32 v[208:209], v[68:69], s[44:45] op_sel_hi:[1,0]
	v_max3_f32 v185, v185, v200, v201
	v_cndmask_b32_e32 v207, v233, v207, vcc
	v_cmp_le_u32_e32 vcc, v189, v175
	v_add_u32_e32 v189, 34, v183
	v_add_u32_e32 v216, 49, v183
	v_cndmask_b32_e32 v206, v233, v206, vcc
	v_cmp_le_u32_e32 vcc, v210, v175
	v_pk_mul_f32 v[210:211], v[70:71], s[44:45] op_sel_hi:[1,0]
	v_max3_f32 v185, v185, v202, v203
	v_cndmask_b32_e32 v209, v233, v209, vcc
	v_cmp_le_u32_e32 vcc, v189, v175
	v_add_u32_e32 v189, 40, v183
	v_max3_f32 v185, v185, v204, v205
	v_cndmask_b32_e32 v208, v233, v208, vcc
	v_cmp_le_u32_e32 vcc, v212, v175
	v_pk_mul_f32 v[212:213], v[72:73], s[44:45] op_sel_hi:[1,0]
	v_add_u32_e32 v218, 51, v183
	v_cndmask_b32_e32 v211, v233, v211, vcc
	v_cmp_le_u32_e32 vcc, v189, v175
	v_add_u32_e32 v189, 42, v183
	v_max3_f32 v185, v185, v206, v207
	v_cndmask_b32_e32 v210, v233, v210, vcc
	v_cmp_le_u32_e32 vcc, v214, v175
	v_pk_mul_f32 v[214:215], v[74:75], s[44:45] op_sel_hi:[1,0]
	v_max3_f32 v185, v185, v208, v209
	v_cndmask_b32_e32 v213, v233, v213, vcc
	v_cmp_le_u32_e32 vcc, v189, v175
	v_add_u32_e32 v189, 48, v183
	v_add_u32_e32 v220, 57, v183
	v_cndmask_b32_e32 v212, v233, v212, vcc
	v_cmp_le_u32_e32 vcc, v216, v175
	v_pk_mul_f32 v[216:217], v[76:77], s[44:45] op_sel_hi:[1,0]
	v_max3_f32 v185, v185, v210, v211
	v_cndmask_b32_e32 v215, v233, v215, vcc
	v_cmp_le_u32_e32 vcc, v189, v175
	v_add_u32_e32 v189, 50, v183
	v_max3_f32 v185, v185, v212, v213
	v_cndmask_b32_e32 v214, v233, v214, vcc
	v_cmp_le_u32_e32 vcc, v218, v175
	v_pk_mul_f32 v[218:219], v[78:79], s[44:45] op_sel_hi:[1,0]
	v_max3_f32 v185, v185, v214, v215
	v_cndmask_b32_e32 v217, v233, v217, vcc
	v_cmp_le_u32_e32 vcc, v189, v175
	v_add_u32_e32 v189, 56, v183
	s_mov_b64 s[2:3], 0
	v_cndmask_b32_e32 v216, v233, v216, vcc
	v_cmp_le_u32_e32 vcc, v220, v175
	v_pk_mul_f32 v[220:221], v[80:81], s[44:45] op_sel_hi:[1,0]
	v_max3_f32 v185, v185, v216, v217
	v_cndmask_b32_e32 v219, v233, v219, vcc
	v_cmp_le_u32_e32 vcc, v189, v175
	v_add_u32_e32 v189, 58, v183
	v_add_u32_e32 v183, 59, v183
	v_cndmask_b32_e32 v218, v233, v218, vcc
	v_cmp_le_u32_e32 vcc, v183, v175
	v_max3_f32 v185, v185, v218, v219
	s_nop 0
	v_cndmask_b32_e32 v221, v233, v221, vcc
	v_cmp_le_u32_e32 vcc, v189, v175
	s_nop 1
	v_cndmask_b32_e32 v220, v233, v220, vcc
	v_max3_f32 v175, v185, v220, v221

; #define MFMA32(a, b, c) __builtin_amdgcn_mfma_f32_32x32x16_bf16((a), (b), (c), 0, 0, 0)
; DI void coop_compute(AttnAcc& a, const bf16x8 (&qf)[8], char* stg, const int lo, const int hi, int lane) {
;     ...
;   for (int hf = 0; hf < 2; ++hf) {
;     const char* kr = stg + (32 * hf + u) * KSTR + 16 * h;
;     bf16x8 kf[8];
; #pragma unroll
;     for (int s = 0; s < 8; ++s) kf[s] = *reinterpret_cast<const bf16x8*>(kr + 32 * s);
;     st[hf] = zero16();
; #pragma unroll
;     for (int s = 0; s < 8; ++s) st[hf] = MFMA32(kf[s], qf[s], st[hf]);
;   }
;   constexpr float C2 = SCALE * 1.4426950408889634f;
;   const bool full = (lo <= 0) && (hi >= 63), empty = lo > hi;
;   float mx = a.m;
;   if (__all(full || empty)) {
; DI void win_block(const Params& p, int it, int tid, int wid, int lane) {
;     ...
;             [&](int j, int& lo_, int& hi_) { const int l0 = t - 511 - 64 * j, h0 = t - 64 * j; lo_ = l0 > 0 ? l0 : 0; hi_ = h0 < 63 ? h0 : 63; }, tid, lane);
.LBB0_257:
	ds_read_b128 v[66:69], v228 offset:35840
	ds_read_b128 v[70:73], v228 offset:35872
	s_lshl_b32 s0, s20, 6
	v_subrev_u32_e32 v177, s0, v188
	v_add_u32_e32 v181, 0xfffffe01, v177
	s_waitcnt lgkmcnt(1)
	v_mfma_f32_32x32x16_bf16 v[82:97], v[66:69], v[122:125], 0
	v_max_i32_e32 v181, 0, v181
	v_min_i32_e32 v185, 63, v177
	v_subrev_u32_e32 v177, 63, v177
	v_cmp_gt_u32_e64 s[0:1], s50, v177
	v_cmp_lt_i32_e32 vcc, v185, v181
	s_or_b64 s[2:3], s[0:1], vcc
	s_waitcnt lgkmcnt(0)
	v_mfma_f32_32x32x16_bf16 v[82:97], v[70:73], v[98:101], v[82:97]
	ds_read_b128 v[66:69], v228 offset:35904
	ds_read_b128 v[70:73], v228 offset:35936
	s_and_b64 s[4:5], s[2:3], exec
	s_mov_b64 s[2:3], -1
	s_cmp_lg_u64 s[4:5], exec
	s_waitcnt lgkmcnt(1)
	v_mfma_f32_32x32x16_bf16 v[82:97], v[66:69], v[102:105], v[82:97]
	s_waitcnt lgkmcnt(0)
	v_mfma_f32_32x32x16_bf16 v[82:97], v[70:73], v[106:109], v[82:97]
	ds_read_b128 v[66:69], v228 offset:35968
	ds_read_b128 v[70:73], v228 offset:36000
	s_waitcnt lgkmcnt(1)
	v_mfma_f32_32x32x16_bf16 v[82:97], v[66:69], v[110:113], v[82:97]
	s_waitcnt lgkmcnt(0)
	v_mfma_f32_32x32x16_bf16 v[82:97], v[70:73], v[114:117], v[82:97]
	ds_read_b128 v[66:69], v228 offset:36032
	ds_read_b128 v[70:73], v228 offset:36064
	s_waitcnt lgkmcnt(1)
	v_mfma_f32_32x32x16_bf16 v[82:97], v[66:69], v[118:121], v[82:97]
	ds_read_b128 v[66:69], v223 offset:35840
	ds_read_b128 v[190:193], v223 offset:35872
	s_waitcnt lgkmcnt(2)
	v_mfma_f32_32x32x16_bf16 v[82:97], v[70:73], v[126:129], v[82:97]
	s_waitcnt lgkmcnt(1)
	v_mfma_f32_32x32x16_bf16 v[66:81], v[66:69], v[122:125], 0
	s_waitcnt lgkmcnt(0)
	v_mfma_f32_32x32x16_bf16 v[66:81], v[190:193], v[98:101], v[66:81]
	ds_read_b128 v[190:193], v223 offset:35904
	ds_read_b128 v[194:197], v223 offset:35936
	s_waitcnt lgkmcnt(1)
	v_mfma_f32_32x32x16_bf16 v[66:81], v[190:193], v[102:105], v[66:81]
	s_waitcnt lgkmcnt(0)
	v_mfma_f32_32x32x16_bf16 v[66:81], v[194:197], v[106:109], v[66:81]
	ds_read_b128 v[190:193], v223 offset:35968
	ds_read_b128 v[194:197], v223 offset:36000
	ds_read_b128 v[250:253], v223 offset:36064
	s_waitcnt lgkmcnt(2)
	v_mfma_f32_32x32x16_bf16 v[66:81], v[190:193], v[110:113], v[66:81]
	ds_read_b128 v[190:193], v223 offset:36032
	s_waitcnt lgkmcnt(2)
	v_mfma_f32_32x32x16_bf16 v[66:81], v[194:197], v[114:117], v[66:81]
	s_waitcnt lgkmcnt(0)
	v_mfma_f32_32x32x16_bf16 v[66:81], v[190:193], v[118:121], v[66:81]
	v_mfma_f32_32x32x16_bf16 v[66:81], v[250:253], v[126:129], v[66:81]
	s_cbranch_scc0 .LBB0_259
; DI void coop_compute(AttnAcc& a, const bf16x8 (&qf)[8], char* stg, const int lo, const int hi, int lane) {
;     ...
;     const unsigned span = empty ? 0u : (unsigned)(hi - lo);
;     const int lo3 = empty ? (1 << 20) : lo - 4 * h;
; #pragma unroll
;     for (int hf = 0; hf < 2; ++hf)
; #pragma unroll
;       for (int i = 0; i < 16; ++i) {
;         const int vc = 32 * hf + (i & 3) + 8 * (i >> 2);
;         const bool ok = (unsigned)(vc - lo3) <= span;
;         const float sv = ok ? st[hf][i] * C2 : NEG;
;         st[hf][i] = sv; mx = fmaxf(mx, sv);
;       }
;   }
	v_sub_u32_e32 v177, v185, v181
	v_sub_u32_e32 v181, v243, v181
	v_cndmask_b32_e64 v177, v177, 0, vcc
	v_cndmask_b32_e32 v181, v181, v232, vcc
	v_pk_mul_f32 v[190:191], v[82:83], s[44:45] op_sel_hi:[1,0]
	v_add_u32_e32 v185, 1, v181
	v_cmp_le_u32_e32 vcc, v181, v177
	v_add_u32_e32 v194, 3, v181
	v_pk_mul_f32 v[192:193], v[84:85], s[44:45] op_sel_hi:[1,0]
	v_cndmask_b32_e32 v190, v233, v190, vcc
	v_cmp_le_u32_e32 vcc, v185, v177
	v_add_u32_e32 v189, 2, v181
	v_add_u32_e32 v196, 9, v181
	v_cndmask_b32_e32 v191, v233, v191, vcc
	v_cmp_le_u32_e32 vcc, v194, v177
	v_pk_mul_f32 v[194:195], v[86:87], s[44:45] op_sel_hi:[1,0]
	v_add_u32_e32 v198, 11, v181
	v_cndmask_b32_e32 v193, v233, v193, vcc
	v_cmp_le_u32_e32 vcc, v189, v177
	v_add_u32_e32 v189, 8, v181
	v_add_u32_e32 v200, 17, v181
	v_cndmask_b32_e32 v192, v233, v192, vcc
	v_cmp_le_u32_e32 vcc, v196, v177
	v_pk_mul_f32 v[196:197], v[88:89], s[44:45] op_sel_hi:[1,0]
	v_add_u32_e32 v202, 19, v181
	v_cndmask_b32_e32 v195, v233, v195, vcc
	v_cmp_le_u32_e32 vcc, v189, v177
	v_add_u32_e32 v189, 10, v181
	v_add_u32_e32 v204, 25, v181
	v_cndmask_b32_e32 v194, v233, v194, vcc
	v_cmp_le_u32_e32 vcc, v198, v177
	v_pk_mul_f32 v[198:199], v[90:91], s[44:45] op_sel_hi:[1,0]
	v_add_u32_e32 v206, 27, v181
	v_cndmask_b32_e32 v197, v233, v197, vcc
	v_cmp_le_u32_e32 vcc, v189, v177
	v_add_u32_e32 v189, 16, v181
	v_add_u32_e32 v208, 33, v181
	v_cndmask_b32_e32 v196, v233, v196, vcc
	v_cmp_le_u32_e32 vcc, v200, v177
	v_pk_mul_f32 v[200:201], v[92:93], s[44:45] op_sel_hi:[1,0]
	v_add_u32_e32 v210, 35, v181
	v_cndmask_b32_e32 v199, v233, v199, vcc
	v_cmp_le_u32_e32 vcc, v189, v177
	v_add_u32_e32 v189, 18, v181
	v_max3_f32 v185, v183, v190, v191
	v_cndmask_b32_e32 v198, v233, v198, vcc
	v_cmp_le_u32_e32 vcc, v202, v177
	v_pk_mul_f32 v[202:203], v[94:95], s[44:45] op_sel_hi:[1,0]
	v_max3_f32 v185, v185, v192, v193
	v_cndmask_b32_e32 v201, v233, v201, vcc
	v_cmp_le_u32_e32 vcc, v189, v177
	v_add_u32_e32 v189, 24, v181
	v_add_u32_e32 v212, 41, v181
	v_cndmask_b32_e32 v200, v233, v200, vcc
	v_cmp_le_u32_e32 vcc, v204, v177
	v_pk_mul_f32 v[204:205], v[96:97], s[44:45] op_sel_hi:[1,0]
	v_max3_f32 v185, v185, v194, v195
	v_cndmask_b32_e32 v203, v233, v203, vcc
	v_cmp_le_u32_e32 vcc, v189, v177
	v_add_u32_e32 v189, 26, v181
	v_max3_f32 v185, v185, v196, v197
	v_cndmask_b32_e32 v202, v233, v202, vcc
	v_cmp_le_u32_e32 vcc, v206, v177
	v_pk_mul_f32 v[206:207], v[66:67], s[44:45] op_sel_hi:[1,0]
	v_add_u32_e32 v214, 43, v181
	v_cndmask_b32_e32 v205, v233, v205, vcc
	v_cmp_le_u32_e32 vcc, v189, v177
	v_add_u32_e32 v189, 32, v181
	v_max3_f32 v185, v185, v198, v199
	v_cndmask_b32_e32 v204, v233, v204, vcc
	v_cmp_le_u32_e32 vcc, v208, v177
	v_pk_mul_f32 v[208:209], v[68:69], s[44:45] op_sel_hi:[1,0]
	v_max3_f32 v185, v185, v200, v201
	v_cndmask_b32_e32 v207, v233, v207, vcc
	v_cmp_le_u32_e32 vcc, v189, v177
	v_add_u32_e32 v189, 34, v181
	v_add_u32_e32 v216, 49, v181
	v_cndmask_b32_e32 v206, v233, v206, vcc
	v_cmp_le_u32_e32 vcc, v210, v177
	v_pk_mul_f32 v[210:211], v[70:71], s[44:45] op_sel_hi:[1,0]
	v_max3_f32 v185, v185, v202, v203
	v_cndmask_b32_e32 v209, v233, v209, vcc
	v_cmp_le_u32_e32 vcc, v189, v177
	v_add_u32_e32 v189, 40, v181
	v_max3_f32 v185, v185, v204, v205
	v_cndmask_b32_e32 v208, v233, v208, vcc
	v_cmp_le_u32_e32 vcc, v212, v177
	v_pk_mul_f32 v[212:213], v[72:73], s[44:45] op_sel_hi:[1,0]
	v_add_u32_e32 v218, 51, v181
	v_cndmask_b32_e32 v211, v233, v211, vcc
	v_cmp_le_u32_e32 vcc, v189, v177
	v_add_u32_e32 v189, 42, v181
	v_max3_f32 v185, v185, v206, v207
	v_cndmask_b32_e32 v210, v233, v210, vcc
	v_cmp_le_u32_e32 vcc, v214, v177
	v_pk_mul_f32 v[214:215], v[74:75], s[44:45] op_sel_hi:[1,0]
	v_max3_f32 v185, v185, v208, v209
	v_cndmask_b32_e32 v213, v233, v213, vcc
	v_cmp_le_u32_e32 vcc, v189, v177
	v_add_u32_e32 v189, 48, v181
	v_add_u32_e32 v220, 57, v181
	v_cndmask_b32_e32 v212, v233, v212, vcc
	v_cmp_le_u32_e32 vcc, v216, v177
	v_pk_mul_f32 v[216:217], v[76:77], s[44:45] op_sel_hi:[1,0]
	v_max3_f32 v185, v185, v210, v211
	v_cndmask_b32_e32 v215, v233, v215, vcc
	v_cmp_le_u32_e32 vcc, v189, v177
	v_add_u32_e32 v189, 50, v181
	v_max3_f32 v185, v185, v212, v213
	v_cndmask_b32_e32 v214, v233, v214, vcc
	v_cmp_le_u32_e32 vcc, v218, v177
	v_pk_mul_f32 v[218:219], v[78:79], s[44:45] op_sel_hi:[1,0]
	v_max3_f32 v185, v185, v214, v215
	v_cndmask_b32_e32 v217, v233, v217, vcc
	v_cmp_le_u32_e32 vcc, v189, v177
	v_add_u32_e32 v189, 56, v181
	s_mov_b64 s[2:3], 0
	v_cndmask_b32_e32 v216, v233, v216, vcc
	v_cmp_le_u32_e32 vcc, v220, v177
	v_pk_mul_f32 v[220:221], v[80:81], s[44:45] op_sel_hi:[1,0]
	v_max3_f32 v185, v185, v216, v217
	v_cndmask_b32_e32 v219, v233, v219, vcc
	v_cmp_le_u32_e32 vcc, v189, v177
	v_add_u32_e32 v189, 58, v181
	v_add_u32_e32 v181, 59, v181
	v_cndmask_b32_e32 v218, v233, v218, vcc
	v_cmp_le_u32_e32 vcc, v181, v177
	v_max3_f32 v185, v185, v218, v219
	s_nop 0
	v_cndmask_b32_e32 v221, v233, v221, vcc
	v_cmp_le_u32_e32 vcc, v189, v177
	s_nop 1
	v_cndmask_b32_e32 v220, v233, v220, vcc
	v_max3_f32 v177, v185, v220, v221
